# saddr-form LDS-DMA + m0 wait-state fix (no loop restructuring)
# baseline (speedup 1.0000x reference)
.LBB0_265:
	ds_read_b128 v[154:157], v161
	ds_read_b128 v[164:167], v161 offset:1024
	ds_read_b128 v[168:171], v161 offset:2048
	ds_read_b128 v[172:175], v161 offset:3072
	ds_read_b128 v[176:179], v162
	ds_read_b128 v[180:183], v162 offset:1024
	ds_read_b128 v[184:187], v162 offset:2048
	ds_read_b128 v[188:191], v162 offset:3072
	s_add_u32 s12, s72, 0xfff00080
	s_addc_u32 s13, s73, -1
	s_cmp_eq_u32 s83, 60
	s_cselect_b32 s77, s55, s13
	s_cselect_b32 s76, s71, s12
	s_cselect_b32 s75, s53, s82
	s_cselect_b32 s74, s80, s81
	s_add_i32 m0, s33, 0xc000
	ds_read_b128 v[192:195], v163
	ds_read_b128 v[196:199], v163 offset:1024
	ds_read_b128 v[200:203], v163 offset:2048
	ds_read_b128 v[204:207], v163 offset:3072
	ds_read_b128 v[208:211], v163 offset:4096
	ds_read_b128 v[212:215], v163 offset:5120
	ds_read_b128 v[216:219], v163 offset:6144
	ds_read_b128 v[220:223], v163 offset:7168
	global_load_lds_dwordx4 v146, s[72:73]
	s_add_i32 m0, s33, 0xe000
	s_nop 0
	global_load_lds_dwordx4 v148, s[72:73]
	s_waitcnt vmcnt(8)
	s_waitcnt lgkmcnt(0)
	s_barrier
	s_setprio 1
	s_waitcnt lgkmcnt(0)
	v_mfma_f32_16x16x32_bf16 v[126:129], v[154:157], v[192:195], v[126:129]
	v_mfma_f32_16x16x32_bf16 v[122:125], v[168:171], v[192:195], v[122:125]
	v_mfma_f32_16x16x32_bf16 v[110:113], v[154:157], v[200:203], v[110:113]
	v_mfma_f32_16x16x32_bf16 v[106:109], v[168:171], v[200:203], v[106:109]
	v_mfma_f32_16x16x32_bf16 v[94:97], v[154:157], v[208:211], v[94:97]
	v_mfma_f32_16x16x32_bf16 v[90:93], v[168:171], v[208:211], v[90:93]
	v_mfma_f32_16x16x32_bf16 v[78:81], v[154:157], v[216:219], v[78:81]
	v_mfma_f32_16x16x32_bf16 v[74:77], v[168:171], v[216:219], v[74:77]
	v_mfma_f32_16x16x32_bf16 v[126:129], v[164:167], v[196:199], v[126:129]
	v_mfma_f32_16x16x32_bf16 v[122:125], v[172:175], v[196:199], v[122:125]
	v_mfma_f32_16x16x32_bf16 v[110:113], v[164:167], v[204:207], v[110:113]
	v_mfma_f32_16x16x32_bf16 v[106:109], v[172:175], v[204:207], v[106:109]
	v_mfma_f32_16x16x32_bf16 v[94:97], v[164:167], v[212:215], v[94:97]
	v_mfma_f32_16x16x32_bf16 v[90:93], v[172:175], v[212:215], v[90:93]
	v_mfma_f32_16x16x32_bf16 v[78:81], v[164:167], v[220:223], v[78:81]
	v_mfma_f32_16x16x32_bf16 v[74:77], v[172:175], v[220:223], v[74:77]
	s_setprio 0
	s_setprio 1
	v_mfma_f32_16x16x32_bf16 v[118:121], v[176:179], v[192:195], v[118:121]
	v_mfma_f32_16x16x32_bf16 v[114:117], v[184:187], v[192:195], v[114:117]
	v_mfma_f32_16x16x32_bf16 v[102:105], v[176:179], v[200:203], v[102:105]
	v_mfma_f32_16x16x32_bf16 v[98:101], v[184:187], v[200:203], v[98:101]
	v_mfma_f32_16x16x32_bf16 v[86:89], v[176:179], v[208:211], v[86:89]
	v_mfma_f32_16x16x32_bf16 v[82:85], v[184:187], v[208:211], v[82:85]
	v_mfma_f32_16x16x32_bf16 v[70:73], v[176:179], v[216:219], v[70:73]
	v_mfma_f32_16x16x32_bf16 v[66:69], v[184:187], v[216:219], v[66:69]
	v_mfma_f32_16x16x32_bf16 v[118:121], v[180:183], v[196:199], v[118:121]
	v_mfma_f32_16x16x32_bf16 v[114:117], v[188:191], v[196:199], v[114:117]
	v_mfma_f32_16x16x32_bf16 v[102:105], v[180:183], v[204:207], v[102:105]
	v_mfma_f32_16x16x32_bf16 v[98:101], v[188:191], v[204:207], v[98:101]
	v_mfma_f32_16x16x32_bf16 v[86:89], v[180:183], v[212:215], v[86:89]
	v_mfma_f32_16x16x32_bf16 v[82:85], v[188:191], v[212:215], v[82:85]
	v_mfma_f32_16x16x32_bf16 v[70:73], v[180:183], v[220:223], v[70:73]
	v_mfma_f32_16x16x32_bf16 v[66:69], v[188:191], v[220:223], v[66:69]
	s_setprio 0
	s_barrier
	s_add_i32 s12, s59, s0
	s_mov_b32 m0, s12
	ds_read_b128 v[192:195], v163 offset:16384
	ds_read_b128 v[196:199], v163 offset:17408
	ds_read_b128 v[200:203], v163 offset:18432
	ds_read_b128 v[204:207], v163 offset:19456
	ds_read_b128 v[208:211], v163 offset:20480
	ds_read_b128 v[212:215], v163 offset:21504
	ds_read_b128 v[216:219], v163 offset:22528
	ds_read_b128 v[220:223], v163 offset:23552
	global_load_lds_dwordx4 v134, s[74:75]
	s_add_i32 m0, s12, 0x2000
	s_add_u32 s12, s74, 0x100000
	s_addc_u32 s13, s75, 0
	s_add_i32 s14, s60, s0
	global_load_lds_dwordx4 v130, s[74:75]
	s_mov_b32 m0, s14
	s_nop 0
	global_load_lds_dwordx4 v134, s[12:13]
	s_add_i32 m0, s14, 0x2000
	s_nop 0
	global_load_lds_dwordx4 v130, s[12:13]
	s_mov_b32 m0, s33
	s_nop 0
	global_load_lds_dwordx4 v136, s[76:77]
	s_mov_b32 m0, s35
	s_nop 0
	global_load_lds_dwordx4 v132, s[76:77]
	s_waitcnt vmcnt(8)
	s_waitcnt lgkmcnt(0)
	s_barrier
	s_setprio 1
	s_waitcnt lgkmcnt(0)
	v_mfma_f32_16x16x32_bf16 v[62:65], v[154:157], v[192:195], v[62:65]
	v_mfma_f32_16x16x32_bf16 v[58:61], v[168:171], v[192:195], v[58:61]
	v_mfma_f32_16x16x32_bf16 v[46:49], v[154:157], v[200:203], v[46:49]
	v_mfma_f32_16x16x32_bf16 v[42:45], v[168:171], v[200:203], v[42:45]
	v_mfma_f32_16x16x32_bf16 v[30:33], v[154:157], v[208:211], v[30:33]
	v_mfma_f32_16x16x32_bf16 v[26:29], v[168:171], v[208:211], v[26:29]
	v_mfma_f32_16x16x32_bf16 v[14:17], v[154:157], v[216:219], v[14:17]
	v_mfma_f32_16x16x32_bf16 v[10:13], v[168:171], v[216:219], v[10:13]
	v_mfma_f32_16x16x32_bf16 v[62:65], v[164:167], v[196:199], v[62:65]
	v_mfma_f32_16x16x32_bf16 v[58:61], v[172:175], v[196:199], v[58:61]
	v_mfma_f32_16x16x32_bf16 v[46:49], v[164:167], v[204:207], v[46:49]
	v_mfma_f32_16x16x32_bf16 v[42:45], v[172:175], v[204:207], v[42:45]
	v_mfma_f32_16x16x32_bf16 v[30:33], v[164:167], v[212:215], v[30:33]
	v_mfma_f32_16x16x32_bf16 v[26:29], v[172:175], v[212:215], v[26:29]
	v_mfma_f32_16x16x32_bf16 v[14:17], v[164:167], v[220:223], v[14:17]
	v_mfma_f32_16x16x32_bf16 v[10:13], v[172:175], v[220:223], v[10:13]
	s_setprio 0
	s_setprio 1
	v_mfma_f32_16x16x32_bf16 v[54:57], v[176:179], v[192:195], v[54:57]
	v_mfma_f32_16x16x32_bf16 v[50:53], v[184:187], v[192:195], v[50:53]
	v_mfma_f32_16x16x32_bf16 v[38:41], v[176:179], v[200:203], v[38:41]
	v_mfma_f32_16x16x32_bf16 v[34:37], v[184:187], v[200:203], v[34:37]
	v_mfma_f32_16x16x32_bf16 v[22:25], v[176:179], v[208:211], v[22:25]
	v_mfma_f32_16x16x32_bf16 v[18:21], v[184:187], v[208:211], v[18:21]
	v_mfma_f32_16x16x32_bf16 v[6:9], v[176:179], v[216:219], v[6:9]
	v_mfma_f32_16x16x32_bf16 v[2:5], v[184:187], v[216:219], v[2:5]
	v_mfma_f32_16x16x32_bf16 v[54:57], v[180:183], v[196:199], v[54:57]
	v_mfma_f32_16x16x32_bf16 v[50:53], v[188:191], v[196:199], v[50:53]
	v_mfma_f32_16x16x32_bf16 v[38:41], v[180:183], v[204:207], v[38:41]
	v_mfma_f32_16x16x32_bf16 v[34:37], v[188:191], v[204:207], v[34:37]
	v_mfma_f32_16x16x32_bf16 v[22:25], v[180:183], v[212:215], v[22:25]
	v_mfma_f32_16x16x32_bf16 v[18:21], v[188:191], v[212:215], v[18:21]
	v_mfma_f32_16x16x32_bf16 v[6:9], v[180:183], v[220:223], v[6:9]
	v_mfma_f32_16x16x32_bf16 v[2:5], v[188:191], v[220:223], v[2:5]
	s_setprio 0
	s_barrier
	s_add_i32 s14, 0, 0x18000
	v_add_u32_e32 v138, s14, v159
	s_add_i32 s15, 0, 0x1c000
	ds_read_b128 v[154:157], v138
	ds_read_b128 v[164:167], v138 offset:1024
	ds_read_b128 v[168:171], v138 offset:2048
	ds_read_b128 v[172:175], v138 offset:3072
	v_add_u32_e32 v138, s15, v159
	ds_read_b128 v[176:179], v138
	ds_read_b128 v[180:183], v138 offset:1024
	ds_read_b128 v[184:187], v138 offset:2048
	ds_read_b128 v[188:191], v138 offset:3072
	s_add_u32 s12, s76, 0x100000
	s_addc_u32 s13, s77, 0
	s_mov_b32 m0, s39
	ds_read_b128 v[192:195], v163 offset:32768
	ds_read_b128 v[196:199], v163 offset:33792
	ds_read_b128 v[200:203], v163 offset:34816
	ds_read_b128 v[204:207], v163 offset:35840
	ds_read_b128 v[208:211], v163 offset:36864
	ds_read_b128 v[212:215], v163 offset:37888
	ds_read_b128 v[216:219], v163 offset:38912
	ds_read_b128 v[220:223], v163 offset:39936
	global_load_lds_dwordx4 v136, s[12:13]
	s_mov_b32 m0, s40
	s_nop 0
	global_load_lds_dwordx4 v132, s[12:13]
	s_waitcnt vmcnt(8)
	s_waitcnt lgkmcnt(0)
	s_barrier
	s_setprio 1
	s_waitcnt lgkmcnt(0)
	v_mfma_f32_16x16x32_bf16 v[126:129], v[154:157], v[192:195], v[126:129]
	v_mfma_f32_16x16x32_bf16 v[122:125], v[168:171], v[192:195], v[122:125]
	v_mfma_f32_16x16x32_bf16 v[110:113], v[154:157], v[200:203], v[110:113]
	v_mfma_f32_16x16x32_bf16 v[106:109], v[168:171], v[200:203], v[106:109]
	v_mfma_f32_16x16x32_bf16 v[94:97], v[154:157], v[208:211], v[94:97]
	v_mfma_f32_16x16x32_bf16 v[90:93], v[168:171], v[208:211], v[90:93]
	v_mfma_f32_16x16x32_bf16 v[78:81], v[154:157], v[216:219], v[78:81]
	v_mfma_f32_16x16x32_bf16 v[74:77], v[168:171], v[216:219], v[74:77]
	v_mfma_f32_16x16x32_bf16 v[126:129], v[164:167], v[196:199], v[126:129]
	v_mfma_f32_16x16x32_bf16 v[122:125], v[172:175], v[196:199], v[122:125]
	v_mfma_f32_16x16x32_bf16 v[110:113], v[164:167], v[204:207], v[110:113]
	v_mfma_f32_16x16x32_bf16 v[106:109], v[172:175], v[204:207], v[106:109]
	v_mfma_f32_16x16x32_bf16 v[94:97], v[164:167], v[212:215], v[94:97]
	v_mfma_f32_16x16x32_bf16 v[90:93], v[172:175], v[212:215], v[90:93]
	v_mfma_f32_16x16x32_bf16 v[78:81], v[164:167], v[220:223], v[78:81]
	v_mfma_f32_16x16x32_bf16 v[74:77], v[172:175], v[220:223], v[74:77]
	s_setprio 0
	s_setprio 1
	v_mfma_f32_16x16x32_bf16 v[118:121], v[176:179], v[192:195], v[118:121]
	v_mfma_f32_16x16x32_bf16 v[114:117], v[184:187], v[192:195], v[114:117]
	v_mfma_f32_16x16x32_bf16 v[102:105], v[176:179], v[200:203], v[102:105]
	v_mfma_f32_16x16x32_bf16 v[98:101], v[184:187], v[200:203], v[98:101]
	v_mfma_f32_16x16x32_bf16 v[86:89], v[176:179], v[208:211], v[86:89]
	v_mfma_f32_16x16x32_bf16 v[82:85], v[184:187], v[208:211], v[82:85]
	v_mfma_f32_16x16x32_bf16 v[70:73], v[176:179], v[216:219], v[70:73]
	v_mfma_f32_16x16x32_bf16 v[66:69], v[184:187], v[216:219], v[66:69]
	v_mfma_f32_16x16x32_bf16 v[118:121], v[180:183], v[196:199], v[118:121]
	v_mfma_f32_16x16x32_bf16 v[114:117], v[188:191], v[196:199], v[114:117]
	v_mfma_f32_16x16x32_bf16 v[102:105], v[180:183], v[204:207], v[102:105]
	v_mfma_f32_16x16x32_bf16 v[98:101], v[188:191], v[204:207], v[98:101]
	v_mfma_f32_16x16x32_bf16 v[86:89], v[180:183], v[212:215], v[86:89]
	v_mfma_f32_16x16x32_bf16 v[82:85], v[188:191], v[212:215], v[82:85]
	v_mfma_f32_16x16x32_bf16 v[70:73], v[180:183], v[220:223], v[70:73]
	v_mfma_f32_16x16x32_bf16 v[66:69], v[188:191], v[220:223], v[66:69]
	s_setprio 0
	s_barrier
	s_add_i32 s12, s14, s0
	s_mov_b32 m0, s12
	ds_read_b128 v[192:195], v163 offset:49152
	ds_read_b128 v[196:199], v163 offset:50176
	ds_read_b128 v[200:203], v163 offset:51200
	ds_read_b128 v[204:207], v163 offset:52224
	ds_read_b128 v[208:211], v163 offset:53248
	ds_read_b128 v[212:215], v163 offset:54272
	ds_read_b128 v[216:219], v163 offset:55296
	ds_read_b128 v[220:223], v163 offset:56320
	s_add_u32 s98, s74, s10
	s_addc_u32 s99, s75, s11
	global_load_lds_dwordx4 v134, s[98:99]
	s_add_i32 m0, s12, 0x2000
	s_add_u32 s12, s74, 0x100080
	s_addc_u32 s13, s75, 0
	s_add_i32 s14, s15, s0
	global_load_lds_dwordx4 v130, s[98:99]
	s_mov_b32 m0, s14
	s_nop 0
	global_load_lds_dwordx4 v134, s[12:13]
	s_add_i32 m0, s14, 0x2000
	s_nop 0
	global_load_lds_dwordx4 v130, s[12:13]
	s_mov_b32 m0, s56
	s_nop 0
	s_add_u32 s100, s76, s10
	s_addc_u32 s101, s77, s11
	global_load_lds_dwordx4 v136, s[100:101]
	s_mov_b32 m0, s57
	s_nop 0
	global_load_lds_dwordx4 v132, s[100:101]
	s_waitcnt vmcnt(8)
	s_waitcnt lgkmcnt(0)
	s_barrier
	s_setprio 1
	s_waitcnt lgkmcnt(0)
	v_mfma_f32_16x16x32_bf16 v[62:65], v[154:157], v[192:195], v[62:65]
	v_mfma_f32_16x16x32_bf16 v[58:61], v[168:171], v[192:195], v[58:61]
	v_mfma_f32_16x16x32_bf16 v[46:49], v[154:157], v[200:203], v[46:49]
	v_mfma_f32_16x16x32_bf16 v[42:45], v[168:171], v[200:203], v[42:45]
	v_mfma_f32_16x16x32_bf16 v[30:33], v[154:157], v[208:211], v[30:33]
	v_mfma_f32_16x16x32_bf16 v[26:29], v[168:171], v[208:211], v[26:29]
	v_mfma_f32_16x16x32_bf16 v[14:17], v[154:157], v[216:219], v[14:17]
	v_mfma_f32_16x16x32_bf16 v[10:13], v[168:171], v[216:219], v[10:13]
	v_mfma_f32_16x16x32_bf16 v[62:65], v[164:167], v[196:199], v[62:65]
	v_mfma_f32_16x16x32_bf16 v[58:61], v[172:175], v[196:199], v[58:61]
	v_mfma_f32_16x16x32_bf16 v[46:49], v[164:167], v[204:207], v[46:49]
	v_mfma_f32_16x16x32_bf16 v[42:45], v[172:175], v[204:207], v[42:45]
	v_mfma_f32_16x16x32_bf16 v[30:33], v[164:167], v[212:215], v[30:33]
	v_mfma_f32_16x16x32_bf16 v[26:29], v[172:175], v[212:215], v[26:29]
	v_mfma_f32_16x16x32_bf16 v[14:17], v[164:167], v[220:223], v[14:17]
	v_mfma_f32_16x16x32_bf16 v[10:13], v[172:175], v[220:223], v[10:13]
	s_setprio 0
	s_setprio 1
	v_mfma_f32_16x16x32_bf16 v[54:57], v[176:179], v[192:195], v[54:57]
	v_mfma_f32_16x16x32_bf16 v[50:53], v[184:187], v[192:195], v[50:53]
	v_mfma_f32_16x16x32_bf16 v[38:41], v[176:179], v[200:203], v[38:41]
	v_mfma_f32_16x16x32_bf16 v[34:37], v[184:187], v[200:203], v[34:37]
	v_mfma_f32_16x16x32_bf16 v[22:25], v[176:179], v[208:211], v[22:25]
	v_mfma_f32_16x16x32_bf16 v[18:21], v[184:187], v[208:211], v[18:21]
	v_mfma_f32_16x16x32_bf16 v[6:9], v[176:179], v[216:219], v[6:9]
	v_mfma_f32_16x16x32_bf16 v[2:5], v[184:187], v[216:219], v[2:5]
	v_mfma_f32_16x16x32_bf16 v[54:57], v[180:183], v[196:199], v[54:57]
	v_mfma_f32_16x16x32_bf16 v[50:53], v[188:191], v[196:199], v[50:53]
	v_mfma_f32_16x16x32_bf16 v[38:41], v[180:183], v[204:207], v[38:41]
	v_mfma_f32_16x16x32_bf16 v[34:37], v[188:191], v[204:207], v[34:37]
	v_mfma_f32_16x16x32_bf16 v[22:25], v[180:183], v[212:215], v[22:25]
	v_mfma_f32_16x16x32_bf16 v[18:21], v[188:191], v[212:215], v[18:21]
	v_mfma_f32_16x16x32_bf16 v[6:9], v[180:183], v[220:223], v[6:9]
	v_mfma_f32_16x16x32_bf16 v[2:5], v[188:191], v[220:223], v[2:5]
	s_setprio 0
	s_barrier
	s_add_i32 s83, s83, 2
	s_add_u32 s72, s72, 0x100
	s_addc_u32 s73, s73, 0
	s_add_u32 s81, s81, 0x100
	s_addc_u32 s82, s82, 0
	s_cmp_gt_u32 s83, 61
	s_cbranch_scc0 .LBB0_265
	s_and_b64 vcc, exec, s[46:47]
	s_cbranch_vccz .LBB0_268
	s_barrier

.LBB0_510:
	ds_read_b128 v[146:149], v152
	ds_read_b128 v[156:159], v152 offset:1024
	ds_read_b128 v[160:163], v152 offset:2048
	ds_read_b128 v[164:167], v152 offset:3072
	ds_read_b128 v[168:171], v153
	ds_read_b128 v[172:175], v153 offset:1024
	ds_read_b128 v[176:179], v153 offset:2048
	ds_read_b128 v[180:183], v153 offset:3072
	s_add_u32 s34, s52, 0xfff00080
	s_addc_u32 s36, s53, -1
	s_cmp_eq_u32 s62, 60
	s_cselect_b32 s67, s45, s36
	s_cselect_b32 s66, s51, s34
	s_cselect_b32 s55, s23, s61
	s_cselect_b32 s54, s59, s60
	s_add_i32 m0, s1, 0xc000
	ds_read_b128 v[184:187], v154
	ds_read_b128 v[188:191], v154 offset:1024
	ds_read_b128 v[192:195], v154 offset:2048
	ds_read_b128 v[196:199], v154 offset:3072
	ds_read_b128 v[206:209], v154 offset:4096
	ds_read_b128 v[210:213], v154 offset:5120
	ds_read_b128 v[214:217], v154 offset:6144
	ds_read_b128 v[218:221], v154 offset:7168
	global_load_lds_dwordx4 v138, s[52:53]
	s_add_i32 m0, s1, 0xe000
	s_nop 0
	global_load_lds_dwordx4 v140, s[52:53]
	s_waitcnt vmcnt(8)
	s_waitcnt lgkmcnt(0)
	s_barrier
	s_setprio 1
	s_waitcnt lgkmcnt(0)
	v_mfma_f32_16x16x32_bf16 v[126:129], v[146:149], v[184:187], v[126:129]
	v_mfma_f32_16x16x32_bf16 v[122:125], v[160:163], v[184:187], v[122:125]
	v_mfma_f32_16x16x32_bf16 v[110:113], v[146:149], v[192:195], v[110:113]
	v_mfma_f32_16x16x32_bf16 v[106:109], v[160:163], v[192:195], v[106:109]
	v_mfma_f32_16x16x32_bf16 v[94:97], v[146:149], v[206:209], v[94:97]
	v_mfma_f32_16x16x32_bf16 v[90:93], v[160:163], v[206:209], v[90:93]
	v_mfma_f32_16x16x32_bf16 v[78:81], v[146:149], v[214:217], v[78:81]
	v_mfma_f32_16x16x32_bf16 v[74:77], v[160:163], v[214:217], v[74:77]
	v_mfma_f32_16x16x32_bf16 v[126:129], v[156:159], v[188:191], v[126:129]
	v_mfma_f32_16x16x32_bf16 v[122:125], v[164:167], v[188:191], v[122:125]
	v_mfma_f32_16x16x32_bf16 v[110:113], v[156:159], v[196:199], v[110:113]
	v_mfma_f32_16x16x32_bf16 v[106:109], v[164:167], v[196:199], v[106:109]
	v_mfma_f32_16x16x32_bf16 v[94:97], v[156:159], v[210:213], v[94:97]
	v_mfma_f32_16x16x32_bf16 v[90:93], v[164:167], v[210:213], v[90:93]
	v_mfma_f32_16x16x32_bf16 v[78:81], v[156:159], v[218:221], v[78:81]
	v_mfma_f32_16x16x32_bf16 v[74:77], v[164:167], v[218:221], v[74:77]
	s_setprio 0
	s_setprio 1
	v_mfma_f32_16x16x32_bf16 v[118:121], v[168:171], v[184:187], v[118:121]
	v_mfma_f32_16x16x32_bf16 v[114:117], v[176:179], v[184:187], v[114:117]
	v_mfma_f32_16x16x32_bf16 v[102:105], v[168:171], v[192:195], v[102:105]
	v_mfma_f32_16x16x32_bf16 v[98:101], v[176:179], v[192:195], v[98:101]
	v_mfma_f32_16x16x32_bf16 v[86:89], v[168:171], v[206:209], v[86:89]
	v_mfma_f32_16x16x32_bf16 v[82:85], v[176:179], v[206:209], v[82:85]
	v_mfma_f32_16x16x32_bf16 v[70:73], v[168:171], v[214:217], v[70:73]
	v_mfma_f32_16x16x32_bf16 v[66:69], v[176:179], v[214:217], v[66:69]
	v_mfma_f32_16x16x32_bf16 v[118:121], v[172:175], v[188:191], v[118:121]
	v_mfma_f32_16x16x32_bf16 v[114:117], v[180:183], v[188:191], v[114:117]
	v_mfma_f32_16x16x32_bf16 v[102:105], v[172:175], v[196:199], v[102:105]
	v_mfma_f32_16x16x32_bf16 v[98:101], v[180:183], v[196:199], v[98:101]
	v_mfma_f32_16x16x32_bf16 v[86:89], v[172:175], v[210:213], v[86:89]
	v_mfma_f32_16x16x32_bf16 v[82:85], v[180:183], v[210:213], v[82:85]
	v_mfma_f32_16x16x32_bf16 v[70:73], v[172:175], v[218:221], v[70:73]
	v_mfma_f32_16x16x32_bf16 v[66:69], v[180:183], v[218:221], v[66:69]
	s_setprio 0
	s_barrier
	s_add_i32 s34, s56, s0
	s_mov_b32 m0, s34
	ds_read_b128 v[184:187], v154 offset:16384
	ds_read_b128 v[188:191], v154 offset:17408
	ds_read_b128 v[192:195], v154 offset:18432
	ds_read_b128 v[196:199], v154 offset:19456
	ds_read_b128 v[206:209], v154 offset:20480
	ds_read_b128 v[210:213], v154 offset:21504
	ds_read_b128 v[214:217], v154 offset:22528
	ds_read_b128 v[218:221], v154 offset:23552
	global_load_lds_dwordx4 v132, s[54:55]
	s_add_i32 m0, s34, 0x2000
	s_add_u32 s36, s54, 0x100000
	s_addc_u32 s37, s55, 0
	s_add_i32 s34, s57, s0
	global_load_lds_dwordx4 v136, s[54:55]
	s_mov_b32 m0, s34
	s_nop 0
	global_load_lds_dwordx4 v132, s[36:37]
	s_add_i32 m0, s34, 0x2000
	s_nop 0
	global_load_lds_dwordx4 v136, s[36:37]
	s_mov_b32 m0, s1
	s_nop 0
	global_load_lds_dwordx4 v130, s[66:67]
	s_mov_b32 m0, s3
	s_nop 0
	global_load_lds_dwordx4 v134, s[66:67]
	s_waitcnt vmcnt(8)
	s_waitcnt lgkmcnt(0)
	s_barrier
	s_setprio 1
	s_waitcnt lgkmcnt(0)
	v_mfma_f32_16x16x32_bf16 v[62:65], v[146:149], v[184:187], v[62:65]
	v_mfma_f32_16x16x32_bf16 v[58:61], v[160:163], v[184:187], v[58:61]
	v_mfma_f32_16x16x32_bf16 v[46:49], v[146:149], v[192:195], v[46:49]
	v_mfma_f32_16x16x32_bf16 v[42:45], v[160:163], v[192:195], v[42:45]
	v_mfma_f32_16x16x32_bf16 v[30:33], v[146:149], v[206:209], v[30:33]
	v_mfma_f32_16x16x32_bf16 v[26:29], v[160:163], v[206:209], v[26:29]
	v_mfma_f32_16x16x32_bf16 v[14:17], v[146:149], v[214:217], v[14:17]
	v_mfma_f32_16x16x32_bf16 v[10:13], v[160:163], v[214:217], v[10:13]
	v_mfma_f32_16x16x32_bf16 v[62:65], v[156:159], v[188:191], v[62:65]
	v_mfma_f32_16x16x32_bf16 v[58:61], v[164:167], v[188:191], v[58:61]
	v_mfma_f32_16x16x32_bf16 v[46:49], v[156:159], v[196:199], v[46:49]
	v_mfma_f32_16x16x32_bf16 v[42:45], v[164:167], v[196:199], v[42:45]
	v_mfma_f32_16x16x32_bf16 v[30:33], v[156:159], v[210:213], v[30:33]
	v_mfma_f32_16x16x32_bf16 v[26:29], v[164:167], v[210:213], v[26:29]
	v_mfma_f32_16x16x32_bf16 v[14:17], v[156:159], v[218:221], v[14:17]
	v_mfma_f32_16x16x32_bf16 v[10:13], v[164:167], v[218:221], v[10:13]
	s_setprio 0
	s_setprio 1
	v_mfma_f32_16x16x32_bf16 v[54:57], v[168:171], v[184:187], v[54:57]
	v_mfma_f32_16x16x32_bf16 v[50:53], v[176:179], v[184:187], v[50:53]
	v_mfma_f32_16x16x32_bf16 v[38:41], v[168:171], v[192:195], v[38:41]
	v_mfma_f32_16x16x32_bf16 v[34:37], v[176:179], v[192:195], v[34:37]
	v_mfma_f32_16x16x32_bf16 v[22:25], v[168:171], v[206:209], v[22:25]
	v_mfma_f32_16x16x32_bf16 v[18:21], v[176:179], v[206:209], v[18:21]
	v_mfma_f32_16x16x32_bf16 v[6:9], v[168:171], v[214:217], v[6:9]
	v_mfma_f32_16x16x32_bf16 v[2:5], v[176:179], v[214:217], v[2:5]
	v_mfma_f32_16x16x32_bf16 v[54:57], v[172:175], v[188:191], v[54:57]
	v_mfma_f32_16x16x32_bf16 v[50:53], v[180:183], v[188:191], v[50:53]
	v_mfma_f32_16x16x32_bf16 v[38:41], v[172:175], v[196:199], v[38:41]
	v_mfma_f32_16x16x32_bf16 v[34:37], v[180:183], v[196:199], v[34:37]
	v_mfma_f32_16x16x32_bf16 v[22:25], v[172:175], v[210:213], v[22:25]
	v_mfma_f32_16x16x32_bf16 v[18:21], v[180:183], v[210:213], v[18:21]
	v_mfma_f32_16x16x32_bf16 v[6:9], v[172:175], v[218:221], v[6:9]
	v_mfma_f32_16x16x32_bf16 v[2:5], v[180:183], v[218:221], v[2:5]
	s_setprio 0
	s_barrier
	s_add_i32 s34, 0, 0x18000
	v_add_u32_e32 v155, s34, v150
	s_add_i32 s63, 0, 0x1c000
	ds_read_b128 v[146:149], v155
	ds_read_b128 v[156:159], v155 offset:1024
	ds_read_b128 v[160:163], v155 offset:2048
	ds_read_b128 v[164:167], v155 offset:3072
	v_add_u32_e32 v155, s63, v150
	ds_read_b128 v[168:171], v155
	ds_read_b128 v[172:175], v155 offset:1024
	ds_read_b128 v[176:179], v155 offset:2048
	ds_read_b128 v[180:183], v155 offset:3072
	s_add_u32 s36, s66, 0x100000
	s_addc_u32 s37, s67, 0
	s_mov_b32 m0, s12
	ds_read_b128 v[184:187], v154 offset:32768
	ds_read_b128 v[188:191], v154 offset:33792
	ds_read_b128 v[192:195], v154 offset:34816
	ds_read_b128 v[196:199], v154 offset:35840
	ds_read_b128 v[206:209], v154 offset:36864
	ds_read_b128 v[210:213], v154 offset:37888
	ds_read_b128 v[214:217], v154 offset:38912
	ds_read_b128 v[218:221], v154 offset:39936
	global_load_lds_dwordx4 v130, s[36:37]
	s_mov_b32 m0, s13
	s_nop 0
	global_load_lds_dwordx4 v134, s[36:37]
	s_waitcnt vmcnt(8)
	s_waitcnt lgkmcnt(0)
	s_barrier
	s_setprio 1
	s_waitcnt lgkmcnt(0)
	v_mfma_f32_16x16x32_bf16 v[126:129], v[146:149], v[184:187], v[126:129]
	v_mfma_f32_16x16x32_bf16 v[122:125], v[160:163], v[184:187], v[122:125]
	v_mfma_f32_16x16x32_bf16 v[110:113], v[146:149], v[192:195], v[110:113]
	v_mfma_f32_16x16x32_bf16 v[106:109], v[160:163], v[192:195], v[106:109]
	v_mfma_f32_16x16x32_bf16 v[94:97], v[146:149], v[206:209], v[94:97]
	v_mfma_f32_16x16x32_bf16 v[90:93], v[160:163], v[206:209], v[90:93]
	v_mfma_f32_16x16x32_bf16 v[78:81], v[146:149], v[214:217], v[78:81]
	v_mfma_f32_16x16x32_bf16 v[74:77], v[160:163], v[214:217], v[74:77]
	v_mfma_f32_16x16x32_bf16 v[126:129], v[156:159], v[188:191], v[126:129]
	v_mfma_f32_16x16x32_bf16 v[122:125], v[164:167], v[188:191], v[122:125]
	v_mfma_f32_16x16x32_bf16 v[110:113], v[156:159], v[196:199], v[110:113]
	v_mfma_f32_16x16x32_bf16 v[106:109], v[164:167], v[196:199], v[106:109]
	v_mfma_f32_16x16x32_bf16 v[94:97], v[156:159], v[210:213], v[94:97]
	v_mfma_f32_16x16x32_bf16 v[90:93], v[164:167], v[210:213], v[90:93]
	v_mfma_f32_16x16x32_bf16 v[78:81], v[156:159], v[218:221], v[78:81]
	v_mfma_f32_16x16x32_bf16 v[74:77], v[164:167], v[218:221], v[74:77]
	s_setprio 0
	s_setprio 1
	v_mfma_f32_16x16x32_bf16 v[118:121], v[168:171], v[184:187], v[118:121]
	v_mfma_f32_16x16x32_bf16 v[114:117], v[176:179], v[184:187], v[114:117]
	v_mfma_f32_16x16x32_bf16 v[102:105], v[168:171], v[192:195], v[102:105]
	v_mfma_f32_16x16x32_bf16 v[98:101], v[176:179], v[192:195], v[98:101]
	v_mfma_f32_16x16x32_bf16 v[86:89], v[168:171], v[206:209], v[86:89]
	v_mfma_f32_16x16x32_bf16 v[82:85], v[176:179], v[206:209], v[82:85]
	v_mfma_f32_16x16x32_bf16 v[70:73], v[168:171], v[214:217], v[70:73]
	v_mfma_f32_16x16x32_bf16 v[66:69], v[176:179], v[214:217], v[66:69]
	v_mfma_f32_16x16x32_bf16 v[118:121], v[172:175], v[188:191], v[118:121]
	v_mfma_f32_16x16x32_bf16 v[114:117], v[180:183], v[188:191], v[114:117]
	v_mfma_f32_16x16x32_bf16 v[102:105], v[172:175], v[196:199], v[102:105]
	v_mfma_f32_16x16x32_bf16 v[98:101], v[180:183], v[196:199], v[98:101]
	v_mfma_f32_16x16x32_bf16 v[86:89], v[172:175], v[210:213], v[86:89]
	v_mfma_f32_16x16x32_bf16 v[82:85], v[180:183], v[210:213], v[82:85]
	v_mfma_f32_16x16x32_bf16 v[70:73], v[172:175], v[218:221], v[70:73]
	v_mfma_f32_16x16x32_bf16 v[66:69], v[180:183], v[218:221], v[66:69]
	s_setprio 0
	s_barrier
	s_add_i32 s34, s34, s0
	s_mov_b32 m0, s34
	ds_read_b128 v[184:187], v154 offset:49152
	ds_read_b128 v[188:191], v154 offset:50176
	ds_read_b128 v[192:195], v154 offset:51200
	ds_read_b128 v[196:199], v154 offset:52224
	ds_read_b128 v[206:209], v154 offset:53248
	ds_read_b128 v[210:213], v154 offset:54272
	ds_read_b128 v[214:217], v154 offset:55296
	ds_read_b128 v[218:221], v154 offset:56320
	s_add_u32 s98, s54, s18
	s_addc_u32 s99, s55, s19
	global_load_lds_dwordx4 v132, s[98:99]
	s_add_i32 m0, s34, 0x2000
	s_add_u32 s36, s54, 0x100080
	s_addc_u32 s37, s55, 0
	s_add_i32 s34, s63, s0
	global_load_lds_dwordx4 v136, s[98:99]
	s_mov_b32 m0, s34
	s_nop 0
	global_load_lds_dwordx4 v132, s[36:37]
	s_add_i32 m0, s34, 0x2000
	s_nop 0
	global_load_lds_dwordx4 v136, s[36:37]
	s_mov_b32 m0, s35
	s_nop 0
	s_add_u32 s100, s66, s18
	s_addc_u32 s101, s67, s19
	global_load_lds_dwordx4 v130, s[100:101]
	s_mov_b32 m0, s39
	s_nop 0
	global_load_lds_dwordx4 v134, s[100:101]
	s_waitcnt vmcnt(8)
	s_waitcnt lgkmcnt(0)
	s_barrier
	s_setprio 1
	s_waitcnt lgkmcnt(0)
	v_mfma_f32_16x16x32_bf16 v[62:65], v[146:149], v[184:187], v[62:65]
	v_mfma_f32_16x16x32_bf16 v[58:61], v[160:163], v[184:187], v[58:61]
	v_mfma_f32_16x16x32_bf16 v[46:49], v[146:149], v[192:195], v[46:49]
	v_mfma_f32_16x16x32_bf16 v[42:45], v[160:163], v[192:195], v[42:45]
	v_mfma_f32_16x16x32_bf16 v[30:33], v[146:149], v[206:209], v[30:33]
	v_mfma_f32_16x16x32_bf16 v[26:29], v[160:163], v[206:209], v[26:29]
	v_mfma_f32_16x16x32_bf16 v[14:17], v[146:149], v[214:217], v[14:17]
	v_mfma_f32_16x16x32_bf16 v[10:13], v[160:163], v[214:217], v[10:13]
	v_mfma_f32_16x16x32_bf16 v[62:65], v[156:159], v[188:191], v[62:65]
	v_mfma_f32_16x16x32_bf16 v[58:61], v[164:167], v[188:191], v[58:61]
	v_mfma_f32_16x16x32_bf16 v[46:49], v[156:159], v[196:199], v[46:49]
	v_mfma_f32_16x16x32_bf16 v[42:45], v[164:167], v[196:199], v[42:45]
	v_mfma_f32_16x16x32_bf16 v[30:33], v[156:159], v[210:213], v[30:33]
	v_mfma_f32_16x16x32_bf16 v[26:29], v[164:167], v[210:213], v[26:29]
	v_mfma_f32_16x16x32_bf16 v[14:17], v[156:159], v[218:221], v[14:17]
	v_mfma_f32_16x16x32_bf16 v[10:13], v[164:167], v[218:221], v[10:13]
	s_setprio 0
	s_setprio 1
	v_mfma_f32_16x16x32_bf16 v[54:57], v[168:171], v[184:187], v[54:57]
	v_mfma_f32_16x16x32_bf16 v[50:53], v[176:179], v[184:187], v[50:53]
	v_mfma_f32_16x16x32_bf16 v[38:41], v[168:171], v[192:195], v[38:41]
	v_mfma_f32_16x16x32_bf16 v[34:37], v[176:179], v[192:195], v[34:37]
	v_mfma_f32_16x16x32_bf16 v[22:25], v[168:171], v[206:209], v[22:25]
	v_mfma_f32_16x16x32_bf16 v[18:21], v[176:179], v[206:209], v[18:21]
	v_mfma_f32_16x16x32_bf16 v[6:9], v[168:171], v[214:217], v[6:9]
	v_mfma_f32_16x16x32_bf16 v[2:5], v[176:179], v[214:217], v[2:5]
	v_mfma_f32_16x16x32_bf16 v[54:57], v[172:175], v[188:191], v[54:57]
	v_mfma_f32_16x16x32_bf16 v[50:53], v[180:183], v[188:191], v[50:53]
	v_mfma_f32_16x16x32_bf16 v[38:41], v[172:175], v[196:199], v[38:41]
	v_mfma_f32_16x16x32_bf16 v[34:37], v[180:183], v[196:199], v[34:37]
	v_mfma_f32_16x16x32_bf16 v[22:25], v[172:175], v[210:213], v[22:25]
	v_mfma_f32_16x16x32_bf16 v[18:21], v[180:183], v[210:213], v[18:21]
	v_mfma_f32_16x16x32_bf16 v[6:9], v[172:175], v[218:221], v[6:9]
	v_mfma_f32_16x16x32_bf16 v[2:5], v[180:183], v[218:221], v[2:5]
	s_setprio 0
	s_barrier
	s_add_i32 s62, s62, 2
	s_add_u32 s60, s60, 0x100
	s_addc_u32 s61, s61, 0
	s_add_u32 s52, s52, 0x100
	s_addc_u32 s53, s53, 0
	s_cmp_gt_u32 s62, 61
	s_cbranch_scc0 .LBB0_510
	s_and_b64 vcc, exec, s[20:21]
	s_cbranch_vccz .LBB0_513
	s_barrier

.LBB0_651:
	ds_read_b128 v[130:133], v210
	ds_read_b128 v[134:137], v210 offset:1024
	ds_read_b128 v[138:141], v210 offset:2048
	ds_read_b128 v[142:145], v210 offset:3072
	ds_read_b128 v[146:149], v211
	ds_read_b128 v[150:153], v211 offset:1024
	ds_read_b128 v[154:157], v211 offset:2048
	ds_read_b128 v[158:161], v211 offset:3072
	s_add_u32 s90, s88, 0x100
	s_addc_u32 s91, s89, 0
	s_cmp_eq_u32 s66, 60
	s_cselect_b32 s95, s79, s91
	s_cselect_b32 s94, s85, s90
	s_cselect_b32 s93, s77, vcc_hi
	s_cselect_b32 s92, s87, vcc_lo
	s_add_i32 m0, s39, 0xc000
	ds_read_b128 v[162:165], v212
	ds_read_b128 v[166:169], v212 offset:1024
	ds_read_b128 v[188:191], v212 offset:2048
	ds_read_b128 v[192:195], v212 offset:3072
	ds_read_b128 v[196:199], v212 offset:4096
	ds_read_b128 v[214:217], v212 offset:5120
	ds_read_b128 v[218:221], v212 offset:6144
	ds_read_b128 v[222:225], v212 offset:7168
	global_load_lds_dwordx4 v180, s[88:89]
	s_add_i32 m0, s39, 0xe000
	s_nop 0
	global_load_lds_dwordx4 v182, s[88:89]
	s_waitcnt vmcnt(8)
	s_waitcnt lgkmcnt(0)
	s_barrier
	s_setprio 1
	s_waitcnt lgkmcnt(0)
	v_mfma_f32_16x16x32_bf16 v[126:129], v[130:133], v[162:165], v[126:129]
	v_mfma_f32_16x16x32_bf16 v[62:65], v[138:141], v[162:165], v[62:65]
	v_mfma_f32_16x16x32_bf16 v[122:125], v[130:133], v[188:191], v[122:125]
	v_mfma_f32_16x16x32_bf16 v[58:61], v[138:141], v[188:191], v[58:61]
	v_mfma_f32_16x16x32_bf16 v[110:113], v[130:133], v[196:199], v[110:113]
	v_mfma_f32_16x16x32_bf16 v[50:53], v[138:141], v[196:199], v[50:53]
	v_mfma_f32_16x16x32_bf16 v[106:109], v[130:133], v[218:221], v[106:109]
	v_mfma_f32_16x16x32_bf16 v[42:45], v[138:141], v[218:221], v[42:45]
	v_mfma_f32_16x16x32_bf16 v[126:129], v[134:137], v[166:169], v[126:129]
	v_mfma_f32_16x16x32_bf16 v[62:65], v[142:145], v[166:169], v[62:65]
	v_mfma_f32_16x16x32_bf16 v[122:125], v[134:137], v[192:195], v[122:125]
	v_mfma_f32_16x16x32_bf16 v[58:61], v[142:145], v[192:195], v[58:61]
	v_mfma_f32_16x16x32_bf16 v[110:113], v[134:137], v[214:217], v[110:113]
	v_mfma_f32_16x16x32_bf16 v[50:53], v[142:145], v[214:217], v[50:53]
	v_mfma_f32_16x16x32_bf16 v[106:109], v[134:137], v[222:225], v[106:109]
	v_mfma_f32_16x16x32_bf16 v[42:45], v[142:145], v[222:225], v[42:45]
	s_setprio 0
	s_setprio 1
	v_mfma_f32_16x16x32_bf16 v[118:121], v[146:149], v[162:165], v[118:121]
	v_mfma_f32_16x16x32_bf16 v[54:57], v[154:157], v[162:165], v[54:57]
	v_mfma_f32_16x16x32_bf16 v[114:117], v[146:149], v[188:191], v[114:117]
	v_mfma_f32_16x16x32_bf16 v[46:49], v[154:157], v[188:191], v[46:49]
	v_mfma_f32_16x16x32_bf16 v[102:105], v[146:149], v[196:199], v[102:105]
	v_mfma_f32_16x16x32_bf16 v[38:41], v[154:157], v[196:199], v[38:41]
	v_mfma_f32_16x16x32_bf16 v[98:101], v[146:149], v[218:221], v[98:101]
	v_mfma_f32_16x16x32_bf16 v[34:37], v[154:157], v[218:221], v[34:37]
	v_mfma_f32_16x16x32_bf16 v[118:121], v[150:153], v[166:169], v[118:121]
	v_mfma_f32_16x16x32_bf16 v[54:57], v[158:161], v[166:169], v[54:57]
	v_mfma_f32_16x16x32_bf16 v[114:117], v[150:153], v[192:195], v[114:117]
	v_mfma_f32_16x16x32_bf16 v[46:49], v[158:161], v[192:195], v[46:49]
	v_mfma_f32_16x16x32_bf16 v[102:105], v[150:153], v[214:217], v[102:105]
	v_mfma_f32_16x16x32_bf16 v[38:41], v[158:161], v[214:217], v[38:41]
	v_mfma_f32_16x16x32_bf16 v[98:101], v[150:153], v[222:225], v[98:101]
	v_mfma_f32_16x16x32_bf16 v[34:37], v[158:161], v[222:225], v[34:37]
	s_setprio 0
	s_barrier
	s_add_i32 s34, s57, s35
	s_mov_b32 m0, s34
	ds_read_b128 v[162:165], v212 offset:16384
	ds_read_b128 v[166:169], v212 offset:17408
	ds_read_b128 v[188:191], v212 offset:18432
	ds_read_b128 v[192:195], v212 offset:19456
	ds_read_b128 v[196:199], v212 offset:20480
	ds_read_b128 v[214:217], v212 offset:21504
	ds_read_b128 v[218:221], v212 offset:22528
	ds_read_b128 v[222:225], v212 offset:23552
	global_load_lds_dwordx4 v172, s[92:93]
	s_add_i32 m0, s34, 0x2000
	s_add_u32 s88, s92, 0x100000
	s_addc_u32 s89, s93, 0
	s_add_i32 s34, s58, s35
	global_load_lds_dwordx4 v176, s[92:93]
	s_mov_b32 m0, s34
	s_nop 0
	global_load_lds_dwordx4 v172, s[88:89]
	s_add_i32 m0, s34, 0x2000
	s_nop 0
	global_load_lds_dwordx4 v176, s[88:89]
	s_mov_b32 m0, s39
	s_nop 0
	global_load_lds_dwordx4 v170, s[94:95]
	s_mov_b32 m0, s62
	s_nop 0
	global_load_lds_dwordx4 v174, s[94:95]
	s_waitcnt vmcnt(8)
	s_waitcnt lgkmcnt(0)
	s_barrier
	s_setprio 1
	s_waitcnt lgkmcnt(0)
	v_mfma_f32_16x16x32_bf16 v[94:97], v[130:133], v[162:165], v[94:97]
	v_mfma_f32_16x16x32_bf16 v[30:33], v[138:141], v[162:165], v[30:33]
	v_mfma_f32_16x16x32_bf16 v[90:93], v[130:133], v[188:191], v[90:93]
	v_mfma_f32_16x16x32_bf16 v[26:29], v[138:141], v[188:191], v[26:29]
	v_mfma_f32_16x16x32_bf16 v[82:85], v[130:133], v[196:199], v[82:85]
	v_mfma_f32_16x16x32_bf16 v[18:21], v[138:141], v[196:199], v[18:21]
	v_mfma_f32_16x16x32_bf16 v[74:77], v[130:133], v[218:221], v[74:77]
	v_mfma_f32_16x16x32_bf16 v[10:13], v[138:141], v[218:221], v[10:13]
	v_mfma_f32_16x16x32_bf16 v[94:97], v[134:137], v[166:169], v[94:97]
	v_mfma_f32_16x16x32_bf16 v[30:33], v[142:145], v[166:169], v[30:33]
	v_mfma_f32_16x16x32_bf16 v[90:93], v[134:137], v[192:195], v[90:93]
	v_mfma_f32_16x16x32_bf16 v[26:29], v[142:145], v[192:195], v[26:29]
	v_mfma_f32_16x16x32_bf16 v[82:85], v[134:137], v[214:217], v[82:85]
	v_mfma_f32_16x16x32_bf16 v[18:21], v[142:145], v[214:217], v[18:21]
	v_mfma_f32_16x16x32_bf16 v[74:77], v[134:137], v[222:225], v[74:77]
	v_mfma_f32_16x16x32_bf16 v[10:13], v[142:145], v[222:225], v[10:13]
	s_setprio 0
	s_setprio 1
	v_mfma_f32_16x16x32_bf16 v[86:89], v[146:149], v[162:165], v[86:89]
	v_mfma_f32_16x16x32_bf16 v[22:25], v[154:157], v[162:165], v[22:25]
	v_mfma_f32_16x16x32_bf16 v[78:81], v[146:149], v[188:191], v[78:81]
	v_mfma_f32_16x16x32_bf16 v[14:17], v[154:157], v[188:191], v[14:17]
	v_mfma_f32_16x16x32_bf16 v[70:73], v[146:149], v[196:199], v[70:73]
	v_mfma_f32_16x16x32_bf16 v[6:9], v[154:157], v[196:199], v[6:9]
	v_mfma_f32_16x16x32_bf16 v[66:69], v[146:149], v[218:221], v[66:69]
	v_mfma_f32_16x16x32_bf16 v[2:5], v[154:157], v[218:221], v[2:5]
	v_mfma_f32_16x16x32_bf16 v[86:89], v[150:153], v[166:169], v[86:89]
	v_mfma_f32_16x16x32_bf16 v[22:25], v[158:161], v[166:169], v[22:25]
	v_mfma_f32_16x16x32_bf16 v[78:81], v[150:153], v[192:195], v[78:81]
	v_mfma_f32_16x16x32_bf16 v[14:17], v[158:161], v[192:195], v[14:17]
	v_mfma_f32_16x16x32_bf16 v[70:73], v[150:153], v[214:217], v[70:73]
	v_mfma_f32_16x16x32_bf16 v[6:9], v[158:161], v[214:217], v[6:9]
	v_mfma_f32_16x16x32_bf16 v[66:69], v[150:153], v[222:225], v[66:69]
	v_mfma_f32_16x16x32_bf16 v[2:5], v[158:161], v[222:225], v[2:5]
	s_setprio 0
	s_barrier
	s_add_i32 s34, 0, 0x18000
	s_add_i32 s67, 0, 0x1c000
	v_add_u32_e32 v142, s34, v207
	v_add_u32_e32 v158, s67, v207
	ds_read_b128 v[130:133], v142
	ds_read_b128 v[134:137], v142 offset:1024
	ds_read_b128 v[138:141], v142 offset:2048
	ds_read_b128 v[142:145], v142 offset:3072
	ds_read_b128 v[146:149], v158
	ds_read_b128 v[150:153], v158 offset:1024
	ds_read_b128 v[154:157], v158 offset:2048
	ds_read_b128 v[158:161], v158 offset:3072
	s_add_u32 s88, s94, 0x100000
	s_addc_u32 s89, s95, 0
	s_mov_b32 m0, s63
	ds_read_b128 v[162:165], v212 offset:32768
	ds_read_b128 v[166:169], v212 offset:33792
	ds_read_b128 v[188:191], v212 offset:34816
	ds_read_b128 v[192:195], v212 offset:35840
	ds_read_b128 v[196:199], v212 offset:36864
	ds_read_b128 v[214:217], v212 offset:37888
	ds_read_b128 v[218:221], v212 offset:38912
	ds_read_b128 v[222:225], v212 offset:39936
	global_load_lds_dwordx4 v170, s[88:89]
	s_mov_b32 m0, s3
	s_nop 0
	global_load_lds_dwordx4 v174, s[88:89]
	s_waitcnt vmcnt(8)
	s_waitcnt lgkmcnt(0)
	s_barrier
	s_setprio 1
	s_waitcnt lgkmcnt(0)
	v_mfma_f32_16x16x32_bf16 v[126:129], v[130:133], v[162:165], v[126:129]
	v_mfma_f32_16x16x32_bf16 v[62:65], v[138:141], v[162:165], v[62:65]
	v_mfma_f32_16x16x32_bf16 v[122:125], v[130:133], v[188:191], v[122:125]
	v_mfma_f32_16x16x32_bf16 v[58:61], v[138:141], v[188:191], v[58:61]
	v_mfma_f32_16x16x32_bf16 v[110:113], v[130:133], v[196:199], v[110:113]
	v_mfma_f32_16x16x32_bf16 v[50:53], v[138:141], v[196:199], v[50:53]
	v_mfma_f32_16x16x32_bf16 v[106:109], v[130:133], v[218:221], v[106:109]
	v_mfma_f32_16x16x32_bf16 v[42:45], v[138:141], v[218:221], v[42:45]
	v_mfma_f32_16x16x32_bf16 v[126:129], v[134:137], v[166:169], v[126:129]
	v_mfma_f32_16x16x32_bf16 v[62:65], v[142:145], v[166:169], v[62:65]
	v_mfma_f32_16x16x32_bf16 v[122:125], v[134:137], v[192:195], v[122:125]
	v_mfma_f32_16x16x32_bf16 v[58:61], v[142:145], v[192:195], v[58:61]
	v_mfma_f32_16x16x32_bf16 v[110:113], v[134:137], v[214:217], v[110:113]
	v_mfma_f32_16x16x32_bf16 v[50:53], v[142:145], v[214:217], v[50:53]
	v_mfma_f32_16x16x32_bf16 v[106:109], v[134:137], v[222:225], v[106:109]
	v_mfma_f32_16x16x32_bf16 v[42:45], v[142:145], v[222:225], v[42:45]
	s_setprio 0
	s_setprio 1
	v_mfma_f32_16x16x32_bf16 v[118:121], v[146:149], v[162:165], v[118:121]
	v_mfma_f32_16x16x32_bf16 v[54:57], v[154:157], v[162:165], v[54:57]
	v_mfma_f32_16x16x32_bf16 v[114:117], v[146:149], v[188:191], v[114:117]
	v_mfma_f32_16x16x32_bf16 v[46:49], v[154:157], v[188:191], v[46:49]
	v_mfma_f32_16x16x32_bf16 v[102:105], v[146:149], v[196:199], v[102:105]
	v_mfma_f32_16x16x32_bf16 v[38:41], v[154:157], v[196:199], v[38:41]
	v_mfma_f32_16x16x32_bf16 v[98:101], v[146:149], v[218:221], v[98:101]
	v_mfma_f32_16x16x32_bf16 v[34:37], v[154:157], v[218:221], v[34:37]
	v_mfma_f32_16x16x32_bf16 v[118:121], v[150:153], v[166:169], v[118:121]
	v_mfma_f32_16x16x32_bf16 v[54:57], v[158:161], v[166:169], v[54:57]
	v_mfma_f32_16x16x32_bf16 v[114:117], v[150:153], v[192:195], v[114:117]
	v_mfma_f32_16x16x32_bf16 v[46:49], v[158:161], v[192:195], v[46:49]
	v_mfma_f32_16x16x32_bf16 v[102:105], v[150:153], v[214:217], v[102:105]
	v_mfma_f32_16x16x32_bf16 v[38:41], v[158:161], v[214:217], v[38:41]
	v_mfma_f32_16x16x32_bf16 v[98:101], v[150:153], v[222:225], v[98:101]
	v_mfma_f32_16x16x32_bf16 v[34:37], v[158:161], v[222:225], v[34:37]
	s_setprio 0
	s_barrier
	s_add_i32 s34, s34, s35
	s_mov_b32 m0, s34
	ds_read_b128 v[162:165], v212 offset:49152
	ds_read_b128 v[166:169], v212 offset:50176
	ds_read_b128 v[188:191], v212 offset:51200
	ds_read_b128 v[192:195], v212 offset:52224
	ds_read_b128 v[196:199], v212 offset:53248
	ds_read_b128 v[214:217], v212 offset:54272
	ds_read_b128 v[218:221], v212 offset:55296
	ds_read_b128 v[222:225], v212 offset:56320
	s_add_u32 s98, s92, s22
	s_addc_u32 s99, s93, s23
	global_load_lds_dwordx4 v172, s[98:99]
	s_add_i32 m0, s34, 0x2000
	s_add_u32 s88, s92, 0x100080
	s_addc_u32 s89, s93, 0
	s_add_i32 s34, s67, s35
	global_load_lds_dwordx4 v176, s[98:99]
	s_mov_b32 m0, s34
	s_nop 0
	global_load_lds_dwordx4 v172, s[88:89]
	s_add_i32 m0, s34, 0x2000
	s_nop 0
	global_load_lds_dwordx4 v176, s[88:89]
	s_mov_b32 m0, s33
	s_nop 0
	s_add_u32 s100, s94, s22
	s_addc_u32 s101, s95, s23
	global_load_lds_dwordx4 v170, s[100:101]
	s_mov_b32 m0, s0
	s_nop 0
	global_load_lds_dwordx4 v174, s[100:101]
	s_waitcnt vmcnt(8)
	s_waitcnt lgkmcnt(0)
	s_barrier
	s_setprio 1
	s_waitcnt lgkmcnt(0)
	v_mfma_f32_16x16x32_bf16 v[94:97], v[130:133], v[162:165], v[94:97]
	v_mfma_f32_16x16x32_bf16 v[30:33], v[138:141], v[162:165], v[30:33]
	v_mfma_f32_16x16x32_bf16 v[90:93], v[130:133], v[188:191], v[90:93]
	v_mfma_f32_16x16x32_bf16 v[26:29], v[138:141], v[188:191], v[26:29]
	v_mfma_f32_16x16x32_bf16 v[82:85], v[130:133], v[196:199], v[82:85]
	v_mfma_f32_16x16x32_bf16 v[18:21], v[138:141], v[196:199], v[18:21]
	v_mfma_f32_16x16x32_bf16 v[74:77], v[130:133], v[218:221], v[74:77]
	v_mfma_f32_16x16x32_bf16 v[10:13], v[138:141], v[218:221], v[10:13]
	v_mfma_f32_16x16x32_bf16 v[94:97], v[134:137], v[166:169], v[94:97]
	v_mfma_f32_16x16x32_bf16 v[30:33], v[142:145], v[166:169], v[30:33]
	v_mfma_f32_16x16x32_bf16 v[90:93], v[134:137], v[192:195], v[90:93]
	v_mfma_f32_16x16x32_bf16 v[26:29], v[142:145], v[192:195], v[26:29]
	v_mfma_f32_16x16x32_bf16 v[82:85], v[134:137], v[214:217], v[82:85]
	v_mfma_f32_16x16x32_bf16 v[18:21], v[142:145], v[214:217], v[18:21]
	v_mfma_f32_16x16x32_bf16 v[74:77], v[134:137], v[222:225], v[74:77]
	v_mfma_f32_16x16x32_bf16 v[10:13], v[142:145], v[222:225], v[10:13]
	s_setprio 0
	s_setprio 1
	v_mfma_f32_16x16x32_bf16 v[86:89], v[146:149], v[162:165], v[86:89]
	v_mfma_f32_16x16x32_bf16 v[22:25], v[154:157], v[162:165], v[22:25]
	v_mfma_f32_16x16x32_bf16 v[78:81], v[146:149], v[188:191], v[78:81]
	v_mfma_f32_16x16x32_bf16 v[14:17], v[154:157], v[188:191], v[14:17]
	v_mfma_f32_16x16x32_bf16 v[70:73], v[146:149], v[196:199], v[70:73]
	v_mfma_f32_16x16x32_bf16 v[6:9], v[154:157], v[196:199], v[6:9]
	v_mfma_f32_16x16x32_bf16 v[66:69], v[146:149], v[218:221], v[66:69]
	v_mfma_f32_16x16x32_bf16 v[2:5], v[154:157], v[218:221], v[2:5]
	v_mfma_f32_16x16x32_bf16 v[86:89], v[150:153], v[166:169], v[86:89]
	v_mfma_f32_16x16x32_bf16 v[22:25], v[158:161], v[166:169], v[22:25]
	v_mfma_f32_16x16x32_bf16 v[78:81], v[150:153], v[192:195], v[78:81]
	v_mfma_f32_16x16x32_bf16 v[14:17], v[158:161], v[192:195], v[14:17]
	v_mfma_f32_16x16x32_bf16 v[70:73], v[150:153], v[214:217], v[70:73]
	v_mfma_f32_16x16x32_bf16 v[6:9], v[158:161], v[214:217], v[6:9]
	v_mfma_f32_16x16x32_bf16 v[66:69], v[150:153], v[222:225], v[66:69]
	v_mfma_f32_16x16x32_bf16 v[2:5], v[158:161], v[222:225], v[2:5]
	s_setprio 0
	s_barrier
	s_add_i32 s66, s66, 2
	s_add_u32 vcc_lo, vcc_lo, 0x100
	s_addc_u32 vcc_hi, vcc_hi, 0
	s_cmp_gt_u32 s66, 61
	s_mov_b64 s[88:89], s[90:91]
	s_cbranch_scc0 .LBB0_651
	s_and_b64 vcc, exec, s[36:37]
	s_cbranch_vccz .LBB0_654
	s_barrier
